# up-projection: next unit's As[1][1] DMA issued before the epilogue stores; first iteration of later units from a copy with three vmcnt(24) waits
# speedup vs baseline: 1.0043x; 1.0024x over previous
; #define PG8_STAGE(bufoff, gbase, voff) do { _Pragma("unroll") for (int _i = 0; _i < 2; ++_i) \
;         __builtin_amdgcn_global_load_lds((const unsigned*)((const char*)(gbase) + (voff)[_i]), (PG8_LAS unsigned*)(lds + (bufoff) + ldsw + _i * 8192), 16, 0, 0); } while (0)
; #define PG8_LDA(dst, b, h) do { _Pragma("unroll") for (int m = 0; m < 4; ++m) _Pragma("unroll") for (int k = 0; k < 2; ++k) dst[m][k] = *(const PG8_LAS bf16x8*)(lds + PG8_SA(b, h) + aoff + m * 2048 + k * 1024); } while (0)
; #define PG8_LDB(dst, b, h) do { _Pragma("unroll") for (int n = 0; n < 2; ++n) _Pragma("unroll") for (int k = 0; k < 2; ++k) dst[n][k] = *(const PG8_LAS bf16x8*)(lds + PG8_SB(b, h) + boff + n * 2048 + k * 1024); } while (0)
; #define PG8_MMA(ai, bj, At, Bt) do { __builtin_amdgcn_s_setprio(1); _Pragma("unroll") for (int m = 0; m < 4; ++m) _Pragma("unroll") for (int n = 0; n < 2; ++n) _Pragma("unroll") for (int k = 0; k < 2; ++k) \
;         acc[ai][bj][m][n] = __builtin_amdgcn_mfma_f32_16x16x32_bf16(Bt[n][k], At[m][k], acc[ai][bj][m][n], 0, 0, 0); __builtin_amdgcn_s_setprio(0); } while (0)
; #define PG8_WAIT_V(n) asm volatile("s_waitcnt vmcnt(" #n ")" ::: "memory")
; #define PG8_WAIT_L(n) asm volatile("s_waitcnt lgkmcnt(" #n ")" ::: "memory")
; #define PG8_BAR __builtin_amdgcn_s_barrier()
; #define PG8_SCHED __builtin_amdgcn_sched_barrier(0)
; template <class Epi, class Sched, bool ALIGN_EPI = false, bool SP2 = false>
; __device__ __forceinline__ void gemm_phase(PG8_LAS unsigned char* lds, const Gemm g, const Sched& S, const Epi& E, const int wid) {
;     ...
;             PG8_LDB(B0, 0, 0); PG8_LDB(B1, 0, 1); PG8_SCHED; PG8_LDA(At, 0, 0); PG8_STAGE(PG8_SA(1, 1), a1 + hsA, voffA);
;             PG8_WAIT_V(8); PG8_WAIT_L(0); PG8_BAR; PG8_MMA(0, 0, At, B0); PG8_MMA(0, 1, At, B1); PG8_BAR; PG8_SCHED;
;             PG8_LDA(At, 0, 1); PG8_STAGE(PG8_SB(0, 0), b2, voffB); PG8_STAGE(PG8_SB(0, 1), b2 + hsB, voffB); PG8_STAGE(PG8_SA(0, 0), a2, voffA);
;             PG8_WAIT_V(8); PG8_WAIT_L(0); PG8_BAR; PG8_MMA(1, 0, At, B0); PG8_MMA(1, 1, At, B1); PG8_BAR; PG8_SCHED;
.Lp9_peel:
	ds_read_b128 v[152:155], v149
	ds_read_b128 v[156:159], v149 offset:1024
	ds_read_b128 v[160:163], v149 offset:2048
	ds_read_b128 v[164:167], v149 offset:3072
	ds_read_b128 v[168:171], v150
	ds_read_b128 v[172:175], v150 offset:1024
	ds_read_b128 v[176:179], v150 offset:2048
	ds_read_b128 v[180:183], v150 offset:3072
	s_add_u32 s8, s56, 0xfffc0080
	s_addc_u32 s9, s57, -1
	s_cmp_eq_u32 s69, 12
	s_cselect_b32 s61, s49, s9
	s_cselect_b32 s60, s65, s8
	s_cselect_b32 s59, s47, s68
	s_cselect_b32 s58, s66, s67
	v_lshl_add_u64 v[146:147], s[56:57], 0, v[138:139]
	s_add_i32 m0, s85, 0xc000
	ds_read_b128 v[184:187], v151
	ds_read_b128 v[188:191], v151 offset:1024
	ds_read_b128 v[192:195], v151 offset:2048
	ds_read_b128 v[196:199], v151 offset:3072
	ds_read_b128 v[200:203], v151 offset:4096
	ds_read_b128 v[204:207], v151 offset:5120
	ds_read_b128 v[208:211], v151 offset:6144
	ds_read_b128 v[212:215], v151 offset:7168
	v_lshl_add_u64 v[146:147], s[56:57], 0, v[140:141]
	s_add_i32 m0, s85, 0xe000
	s_nop 0
	s_waitcnt vmcnt(24)
	s_waitcnt lgkmcnt(0)
	s_barrier
	s_setprio 1
	s_waitcnt lgkmcnt(0)
	v_mfma_f32_16x16x32_bf16 v[126:129], v[152:155], v[184:187], v[126:129]
	v_mfma_f32_16x16x32_bf16 v[122:125], v[160:163], v[184:187], v[122:125]
	v_mfma_f32_16x16x32_bf16 v[110:113], v[152:155], v[192:195], v[110:113]
	v_mfma_f32_16x16x32_bf16 v[106:109], v[160:163], v[192:195], v[106:109]
	v_mfma_f32_16x16x32_bf16 v[94:97], v[152:155], v[200:203], v[94:97]
	v_mfma_f32_16x16x32_bf16 v[90:93], v[160:163], v[200:203], v[90:93]
	v_mfma_f32_16x16x32_bf16 v[78:81], v[152:155], v[208:211], v[78:81]
	v_mfma_f32_16x16x32_bf16 v[74:77], v[160:163], v[208:211], v[74:77]
	v_mfma_f32_16x16x32_bf16 v[126:129], v[156:159], v[188:191], v[126:129]
	v_mfma_f32_16x16x32_bf16 v[122:125], v[164:167], v[188:191], v[122:125]
	v_mfma_f32_16x16x32_bf16 v[110:113], v[156:159], v[196:199], v[110:113]
	v_mfma_f32_16x16x32_bf16 v[106:109], v[164:167], v[196:199], v[106:109]
	v_mfma_f32_16x16x32_bf16 v[94:97], v[156:159], v[204:207], v[94:97]
	v_mfma_f32_16x16x32_bf16 v[90:93], v[164:167], v[204:207], v[90:93]
	v_mfma_f32_16x16x32_bf16 v[78:81], v[156:159], v[212:215], v[78:81]
	v_mfma_f32_16x16x32_bf16 v[74:77], v[164:167], v[212:215], v[74:77]
	s_setprio 0
	s_setprio 1
	v_mfma_f32_16x16x32_bf16 v[118:121], v[168:171], v[184:187], v[118:121]
	v_mfma_f32_16x16x32_bf16 v[114:117], v[176:179], v[184:187], v[114:117]
	v_mfma_f32_16x16x32_bf16 v[102:105], v[168:171], v[192:195], v[102:105]
	v_mfma_f32_16x16x32_bf16 v[98:101], v[176:179], v[192:195], v[98:101]
	v_mfma_f32_16x16x32_bf16 v[86:89], v[168:171], v[200:203], v[86:89]
	v_mfma_f32_16x16x32_bf16 v[82:85], v[176:179], v[200:203], v[82:85]
	v_mfma_f32_16x16x32_bf16 v[70:73], v[168:171], v[208:211], v[70:73]
	v_mfma_f32_16x16x32_bf16 v[66:69], v[176:179], v[208:211], v[66:69]
	v_mfma_f32_16x16x32_bf16 v[118:121], v[172:175], v[188:191], v[118:121]
	v_mfma_f32_16x16x32_bf16 v[114:117], v[180:183], v[188:191], v[114:117]
	v_mfma_f32_16x16x32_bf16 v[102:105], v[172:175], v[196:199], v[102:105]
	v_mfma_f32_16x16x32_bf16 v[98:101], v[180:183], v[196:199], v[98:101]
	v_mfma_f32_16x16x32_bf16 v[86:89], v[172:175], v[204:207], v[86:89]
	v_mfma_f32_16x16x32_bf16 v[82:85], v[180:183], v[204:207], v[82:85]
	v_mfma_f32_16x16x32_bf16 v[70:73], v[172:175], v[212:215], v[70:73]
	v_mfma_f32_16x16x32_bf16 v[66:69], v[180:183], v[212:215], v[66:69]
	s_setprio 0
	s_barrier
	s_add_i32 s8, s35, s28
	v_lshl_add_u64 v[146:147], s[58:59], 0, v[134:135]
	s_mov_b32 m0, s8
	ds_read_b128 v[184:187], v151 offset:16384
	ds_read_b128 v[188:191], v151 offset:17408
	ds_read_b128 v[192:195], v151 offset:18432
	ds_read_b128 v[196:199], v151 offset:19456
	ds_read_b128 v[200:203], v151 offset:20480
	ds_read_b128 v[204:207], v151 offset:21504
	ds_read_b128 v[208:211], v151 offset:22528
	ds_read_b128 v[212:215], v151 offset:23552
	global_load_lds_dwordx4 v[146:147], off
	s_add_i32 m0, s8, 0x2000
	s_add_u32 s24, s58, 0x40000
	v_lshl_add_u64 v[216:217], s[58:59], 0, v[130:131]
	s_addc_u32 s25, s59, 0
	s_add_i32 s8, s36, s28
	global_load_lds_dwordx4 v[216:217], off
	v_lshl_add_u64 v[218:219], s[24:25], 0, v[134:135]
	s_mov_b32 m0, s8
	v_lshl_add_u64 v[220:221], s[60:61], 0, v[132:133]
	global_load_lds_dwordx4 v[218:219], off
	v_lshl_add_u64 v[218:219], s[24:25], 0, v[130:131]
	s_add_i32 m0, s8, 0x2000
	s_nop 0
	global_load_lds_dwordx4 v[218:219], off
	v_lshl_add_u64 v[218:219], s[60:61], 0, v[136:137]
	s_mov_b32 m0, s85
	s_nop 0
	global_load_lds_dwordx4 v[218:219], off
	s_mov_b32 m0, s17
	s_nop 0
	global_load_lds_dwordx4 v[220:221], off
	s_waitcnt vmcnt(24)
	s_waitcnt lgkmcnt(0)
	s_barrier
; #define PG8_STAGE(bufoff, gbase, voff) do { _Pragma("unroll") for (int _i = 0; _i < 2; ++_i) \
;         __builtin_amdgcn_global_load_lds((const unsigned*)((const char*)(gbase) + (voff)[_i]), (PG8_LAS unsigned*)(lds + (bufoff) + ldsw + _i * 8192), 16, 0, 0); } while (0)
; #define PG8_LDA(dst, b, h) do { _Pragma("unroll") for (int m = 0; m < 4; ++m) _Pragma("unroll") for (int k = 0; k < 2; ++k) dst[m][k] = *(const PG8_LAS bf16x8*)(lds + PG8_SA(b, h) + aoff + m * 2048 + k * 1024); } while (0)
; #define PG8_LDB(dst, b, h) do { _Pragma("unroll") for (int n = 0; n < 2; ++n) _Pragma("unroll") for (int k = 0; k < 2; ++k) dst[n][k] = *(const PG8_LAS bf16x8*)(lds + PG8_SB(b, h) + boff + n * 2048 + k * 1024); } while (0)
; #define PG8_MMA(ai, bj, At, Bt) do { __builtin_amdgcn_s_setprio(1); _Pragma("unroll") for (int m = 0; m < 4; ++m) _Pragma("unroll") for (int n = 0; n < 2; ++n) _Pragma("unroll") for (int k = 0; k < 2; ++k) \
;         acc[ai][bj][m][n] = __builtin_amdgcn_mfma_f32_16x16x32_bf16(Bt[n][k], At[m][k], acc[ai][bj][m][n], 0, 0, 0); __builtin_amdgcn_s_setprio(0); } while (0)
; #define PG8_WAIT_V(n) asm volatile("s_waitcnt vmcnt(" #n ")" ::: "memory")
; #define PG8_WAIT_L(n) asm volatile("s_waitcnt lgkmcnt(" #n ")" ::: "memory")
; #define PG8_BAR __builtin_amdgcn_s_barrier()
; #define PG8_SCHED __builtin_amdgcn_sched_barrier(0)
; template <class Epi, class Sched, bool ALIGN_EPI = false, bool SP2 = false>
; __device__ __forceinline__ void gemm_phase(PG8_LAS unsigned char* lds, const Gemm g, const Sched& S, const Epi& E, const int wid) {
;     ...
;             PG8_WAIT_V(8); PG8_WAIT_L(0); PG8_BAR; PG8_MMA(1, 0, At, B0); PG8_MMA(1, 1, At, B1); PG8_BAR; PG8_SCHED;
;             PG8_LDB(B0, 1, 0); PG8_LDB(B1, 1, 1); PG8_SCHED; PG8_LDA(At, 1, 0); PG8_STAGE(PG8_SA(0, 1), a2 + hsA, voffA);
;             PG8_WAIT_V(8); PG8_WAIT_L(0); PG8_BAR; PG8_MMA(0, 0, At, B0); PG8_MMA(0, 1, At, B1); PG8_BAR; PG8_SCHED;
	s_setprio 1
	s_waitcnt lgkmcnt(0)
	v_mfma_f32_16x16x32_bf16 v[62:65], v[152:155], v[184:187], v[62:65]
	v_mfma_f32_16x16x32_bf16 v[58:61], v[160:163], v[184:187], v[58:61]
	v_mfma_f32_16x16x32_bf16 v[46:49], v[152:155], v[192:195], v[46:49]
	v_mfma_f32_16x16x32_bf16 v[42:45], v[160:163], v[192:195], v[42:45]
	v_mfma_f32_16x16x32_bf16 v[30:33], v[152:155], v[200:203], v[30:33]
	v_mfma_f32_16x16x32_bf16 v[26:29], v[160:163], v[200:203], v[26:29]
	v_mfma_f32_16x16x32_bf16 v[14:17], v[152:155], v[208:211], v[14:17]
	v_mfma_f32_16x16x32_bf16 v[10:13], v[160:163], v[208:211], v[10:13]
	v_mfma_f32_16x16x32_bf16 v[62:65], v[156:159], v[188:191], v[62:65]
	v_mfma_f32_16x16x32_bf16 v[58:61], v[164:167], v[188:191], v[58:61]
	v_mfma_f32_16x16x32_bf16 v[46:49], v[156:159], v[196:199], v[46:49]
	v_mfma_f32_16x16x32_bf16 v[42:45], v[164:167], v[196:199], v[42:45]
	v_mfma_f32_16x16x32_bf16 v[30:33], v[156:159], v[204:207], v[30:33]
	v_mfma_f32_16x16x32_bf16 v[26:29], v[164:167], v[204:207], v[26:29]
	v_mfma_f32_16x16x32_bf16 v[14:17], v[156:159], v[212:215], v[14:17]
	v_mfma_f32_16x16x32_bf16 v[10:13], v[164:167], v[212:215], v[10:13]
	s_setprio 0
	s_setprio 1
	v_mfma_f32_16x16x32_bf16 v[54:57], v[168:171], v[184:187], v[54:57]
	v_mfma_f32_16x16x32_bf16 v[50:53], v[176:179], v[184:187], v[50:53]
	v_mfma_f32_16x16x32_bf16 v[38:41], v[168:171], v[192:195], v[38:41]
	v_mfma_f32_16x16x32_bf16 v[34:37], v[176:179], v[192:195], v[34:37]
	v_mfma_f32_16x16x32_bf16 v[22:25], v[168:171], v[200:203], v[22:25]
	v_mfma_f32_16x16x32_bf16 v[18:21], v[176:179], v[200:203], v[18:21]
	v_mfma_f32_16x16x32_bf16 v[6:9], v[168:171], v[208:211], v[6:9]
	v_mfma_f32_16x16x32_bf16 v[2:5], v[176:179], v[208:211], v[2:5]
	v_mfma_f32_16x16x32_bf16 v[54:57], v[172:175], v[188:191], v[54:57]
	v_mfma_f32_16x16x32_bf16 v[50:53], v[180:183], v[188:191], v[50:53]
	v_mfma_f32_16x16x32_bf16 v[38:41], v[172:175], v[196:199], v[38:41]
	v_mfma_f32_16x16x32_bf16 v[34:37], v[180:183], v[196:199], v[34:37]
	v_mfma_f32_16x16x32_bf16 v[22:25], v[172:175], v[204:207], v[22:25]
	v_mfma_f32_16x16x32_bf16 v[18:21], v[180:183], v[204:207], v[18:21]
	v_mfma_f32_16x16x32_bf16 v[6:9], v[172:175], v[212:215], v[6:9]
	v_mfma_f32_16x16x32_bf16 v[2:5], v[180:183], v[212:215], v[2:5]
	s_setprio 0
	s_barrier
	s_add_i32 s8, 0, 0x18000
	s_add_i32 s9, 0, 0x1c000
	v_add_u32_e32 v164, s8, v148
	v_add_u32_e32 v180, s9, v148
	ds_read_b128 v[152:155], v164
	ds_read_b128 v[156:159], v164 offset:1024
	ds_read_b128 v[160:163], v164 offset:2048
	ds_read_b128 v[164:167], v164 offset:3072
	ds_read_b128 v[168:171], v180
	ds_read_b128 v[172:175], v180 offset:1024
	ds_read_b128 v[176:179], v180 offset:2048
	ds_read_b128 v[180:183], v180 offset:3072
	s_add_u32 s24, s60, 0x40000
	s_addc_u32 s25, s61, 0
	s_mov_b32 m0, s18
	v_lshl_add_u64 v[222:223], s[24:25], 0, v[136:137]
	ds_read_b128 v[184:187], v151 offset:32768
	ds_read_b128 v[188:191], v151 offset:33792
	ds_read_b128 v[192:195], v151 offset:34816
	ds_read_b128 v[196:199], v151 offset:35840
	ds_read_b128 v[200:203], v151 offset:36864
	ds_read_b128 v[204:207], v151 offset:37888
	ds_read_b128 v[208:211], v151 offset:38912
	ds_read_b128 v[212:215], v151 offset:39936
	global_load_lds_dwordx4 v[222:223], off
	v_lshl_add_u64 v[222:223], s[24:25], 0, v[132:133]
	s_mov_b32 m0, s19
	s_nop 0
	global_load_lds_dwordx4 v[222:223], off
	s_waitcnt vmcnt(24)
	s_waitcnt lgkmcnt(0)
	s_barrier
	s_setprio 1
	s_waitcnt lgkmcnt(0)
	v_mfma_f32_16x16x32_bf16 v[126:129], v[152:155], v[184:187], v[126:129]
	v_mfma_f32_16x16x32_bf16 v[122:125], v[160:163], v[184:187], v[122:125]
	v_mfma_f32_16x16x32_bf16 v[110:113], v[152:155], v[192:195], v[110:113]
	v_mfma_f32_16x16x32_bf16 v[106:109], v[160:163], v[192:195], v[106:109]
	v_mfma_f32_16x16x32_bf16 v[94:97], v[152:155], v[200:203], v[94:97]
	v_mfma_f32_16x16x32_bf16 v[90:93], v[160:163], v[200:203], v[90:93]
	v_mfma_f32_16x16x32_bf16 v[78:81], v[152:155], v[208:211], v[78:81]
	v_mfma_f32_16x16x32_bf16 v[74:77], v[160:163], v[208:211], v[74:77]
	v_mfma_f32_16x16x32_bf16 v[126:129], v[156:159], v[188:191], v[126:129]
	v_mfma_f32_16x16x32_bf16 v[122:125], v[164:167], v[188:191], v[122:125]
	v_mfma_f32_16x16x32_bf16 v[110:113], v[156:159], v[196:199], v[110:113]
	v_mfma_f32_16x16x32_bf16 v[106:109], v[164:167], v[196:199], v[106:109]
	v_mfma_f32_16x16x32_bf16 v[94:97], v[156:159], v[204:207], v[94:97]
	v_mfma_f32_16x16x32_bf16 v[90:93], v[164:167], v[204:207], v[90:93]
	v_mfma_f32_16x16x32_bf16 v[78:81], v[156:159], v[212:215], v[78:81]
	v_mfma_f32_16x16x32_bf16 v[74:77], v[164:167], v[212:215], v[74:77]
	s_setprio 0
	s_setprio 1
	v_mfma_f32_16x16x32_bf16 v[118:121], v[168:171], v[184:187], v[118:121]
	v_mfma_f32_16x16x32_bf16 v[114:117], v[176:179], v[184:187], v[114:117]
	v_mfma_f32_16x16x32_bf16 v[102:105], v[168:171], v[192:195], v[102:105]
	v_mfma_f32_16x16x32_bf16 v[98:101], v[176:179], v[192:195], v[98:101]
	v_mfma_f32_16x16x32_bf16 v[86:89], v[168:171], v[200:203], v[86:89]
	v_mfma_f32_16x16x32_bf16 v[82:85], v[176:179], v[200:203], v[82:85]
	v_mfma_f32_16x16x32_bf16 v[70:73], v[168:171], v[208:211], v[70:73]
	v_mfma_f32_16x16x32_bf16 v[66:69], v[176:179], v[208:211], v[66:69]
	v_mfma_f32_16x16x32_bf16 v[118:121], v[172:175], v[188:191], v[118:121]
	v_mfma_f32_16x16x32_bf16 v[114:117], v[180:183], v[188:191], v[114:117]
	v_mfma_f32_16x16x32_bf16 v[102:105], v[172:175], v[196:199], v[102:105]
	v_mfma_f32_16x16x32_bf16 v[98:101], v[180:183], v[196:199], v[98:101]
	v_mfma_f32_16x16x32_bf16 v[86:89], v[172:175], v[204:207], v[86:89]
	v_mfma_f32_16x16x32_bf16 v[82:85], v[180:183], v[204:207], v[82:85]
	v_mfma_f32_16x16x32_bf16 v[70:73], v[172:175], v[212:215], v[70:73]
	v_mfma_f32_16x16x32_bf16 v[66:69], v[180:183], v[212:215], v[66:69]
	s_setprio 0
	s_barrier
; #define PG8_STAGE(bufoff, gbase, voff) do { _Pragma("unroll") for (int _i = 0; _i < 2; ++_i) \
;         __builtin_amdgcn_global_load_lds((const unsigned*)((const char*)(gbase) + (voff)[_i]), (PG8_LAS unsigned*)(lds + (bufoff) + ldsw + _i * 8192), 16, 0, 0); } while (0)
; #define PG8_LDA(dst, b, h) do { _Pragma("unroll") for (int m = 0; m < 4; ++m) _Pragma("unroll") for (int k = 0; k < 2; ++k) dst[m][k] = *(const PG8_LAS bf16x8*)(lds + PG8_SA(b, h) + aoff + m * 2048 + k * 1024); } while (0)
; #define PG8_MMA(ai, bj, At, Bt) do { __builtin_amdgcn_s_setprio(1); _Pragma("unroll") for (int m = 0; m < 4; ++m) _Pragma("unroll") for (int n = 0; n < 2; ++n) _Pragma("unroll") for (int k = 0; k < 2; ++k) \
;         acc[ai][bj][m][n] = __builtin_amdgcn_mfma_f32_16x16x32_bf16(Bt[n][k], At[m][k], acc[ai][bj][m][n], 0, 0, 0); __builtin_amdgcn_s_setprio(0); } while (0)
; #define PG8_WAIT_V(n) asm volatile("s_waitcnt vmcnt(" #n ")" ::: "memory")
; #define PG8_WAIT_L(n) asm volatile("s_waitcnt lgkmcnt(" #n ")" ::: "memory")
; #define PG8_BAR __builtin_amdgcn_s_barrier()
; #define PG8_SCHED __builtin_amdgcn_sched_barrier(0)
; template <class Epi, class Sched, bool ALIGN_EPI = false, bool SP2 = false>
; __device__ __forceinline__ void gemm_phase(PG8_LAS unsigned char* lds, const Gemm g, const Sched& S, const Epi& E, const int wid) {
;     ...
;             PG8_LDA(At, 1, 1); PG8_STAGE(PG8_SB(1, 0), b3, voffB); PG8_STAGE(PG8_SB(1, 1), b3 + hsB, voffB); PG8_STAGE(PG8_SA(1, 0), a3, voffA);
;             PG8_WAIT_V(8); PG8_WAIT_L(0); PG8_BAR; PG8_MMA(1, 0, At, B0); PG8_MMA(1, 1, At, B1); PG8_BAR; PG8_SCHED;
	s_add_i32 s8, s8, s28
	v_lshl_add_u64 v[146:147], v[146:147], 0, s[20:21]
	s_mov_b32 m0, s8
	ds_read_b128 v[184:187], v151 offset:49152
	ds_read_b128 v[188:191], v151 offset:50176
	ds_read_b128 v[192:195], v151 offset:51200
	ds_read_b128 v[196:199], v151 offset:52224
	ds_read_b128 v[200:203], v151 offset:53248
	ds_read_b128 v[204:207], v151 offset:54272
	ds_read_b128 v[208:211], v151 offset:55296
	ds_read_b128 v[212:215], v151 offset:56320
	global_load_lds_dwordx4 v[146:147], off
	s_add_i32 m0, s8, 0x2000
	s_add_u32 s24, s58, 0x40080
	v_lshl_add_u64 v[146:147], v[216:217], 0, s[20:21]
	s_addc_u32 s25, s59, 0
	s_add_i32 s8, s9, s28
	global_load_lds_dwordx4 v[146:147], off
	v_lshl_add_u64 v[146:147], s[24:25], 0, v[134:135]
	s_mov_b32 m0, s8
	s_nop 0
	global_load_lds_dwordx4 v[146:147], off
	v_lshl_add_u64 v[146:147], s[24:25], 0, v[130:131]
	s_add_i32 m0, s8, 0x2000
	s_nop 0
	global_load_lds_dwordx4 v[146:147], off
	v_lshl_add_u64 v[146:147], v[218:219], 0, s[20:21]
	s_mov_b32 m0, s27
	s_nop 0
	global_load_lds_dwordx4 v[146:147], off
	v_lshl_add_u64 v[146:147], v[220:221], 0, s[20:21]
	s_mov_b32 m0, s31
	s_nop 0
	global_load_lds_dwordx4 v[146:147], off
	s_waitcnt vmcnt(8)
	s_waitcnt lgkmcnt(0)
	s_barrier
	s_setprio 1
	s_waitcnt lgkmcnt(0)
	v_mfma_f32_16x16x32_bf16 v[62:65], v[152:155], v[184:187], v[62:65]
	v_mfma_f32_16x16x32_bf16 v[58:61], v[160:163], v[184:187], v[58:61]
	v_mfma_f32_16x16x32_bf16 v[46:49], v[152:155], v[192:195], v[46:49]
	v_mfma_f32_16x16x32_bf16 v[42:45], v[160:163], v[192:195], v[42:45]
	v_mfma_f32_16x16x32_bf16 v[30:33], v[152:155], v[200:203], v[30:33]
	v_mfma_f32_16x16x32_bf16 v[26:29], v[160:163], v[200:203], v[26:29]
	v_mfma_f32_16x16x32_bf16 v[14:17], v[152:155], v[208:211], v[14:17]
	v_mfma_f32_16x16x32_bf16 v[10:13], v[160:163], v[208:211], v[10:13]
	v_mfma_f32_16x16x32_bf16 v[62:65], v[156:159], v[188:191], v[62:65]
	v_mfma_f32_16x16x32_bf16 v[58:61], v[164:167], v[188:191], v[58:61]
	v_mfma_f32_16x16x32_bf16 v[46:49], v[156:159], v[196:199], v[46:49]
	v_mfma_f32_16x16x32_bf16 v[42:45], v[164:167], v[196:199], v[42:45]
	v_mfma_f32_16x16x32_bf16 v[30:33], v[156:159], v[204:207], v[30:33]
	v_mfma_f32_16x16x32_bf16 v[26:29], v[164:167], v[204:207], v[26:29]
	v_mfma_f32_16x16x32_bf16 v[14:17], v[156:159], v[212:215], v[14:17]
	v_mfma_f32_16x16x32_bf16 v[10:13], v[164:167], v[212:215], v[10:13]
	s_setprio 0
	s_setprio 1
	v_mfma_f32_16x16x32_bf16 v[54:57], v[168:171], v[184:187], v[54:57]
	v_mfma_f32_16x16x32_bf16 v[50:53], v[176:179], v[184:187], v[50:53]
	v_mfma_f32_16x16x32_bf16 v[38:41], v[168:171], v[192:195], v[38:41]
	v_mfma_f32_16x16x32_bf16 v[34:37], v[176:179], v[192:195], v[34:37]
	v_mfma_f32_16x16x32_bf16 v[22:25], v[168:171], v[200:203], v[22:25]
	v_mfma_f32_16x16x32_bf16 v[18:21], v[176:179], v[200:203], v[18:21]
	v_mfma_f32_16x16x32_bf16 v[6:9], v[168:171], v[208:211], v[6:9]
	v_mfma_f32_16x16x32_bf16 v[2:5], v[176:179], v[208:211], v[2:5]
	v_mfma_f32_16x16x32_bf16 v[54:57], v[172:175], v[188:191], v[54:57]
	v_mfma_f32_16x16x32_bf16 v[50:53], v[180:183], v[188:191], v[50:53]
	v_mfma_f32_16x16x32_bf16 v[38:41], v[172:175], v[196:199], v[38:41]
	v_mfma_f32_16x16x32_bf16 v[34:37], v[180:183], v[196:199], v[34:37]
	v_mfma_f32_16x16x32_bf16 v[22:25], v[172:175], v[204:207], v[22:25]
	v_mfma_f32_16x16x32_bf16 v[18:21], v[180:183], v[204:207], v[18:21]
	v_mfma_f32_16x16x32_bf16 v[6:9], v[172:175], v[212:215], v[6:9]
	v_mfma_f32_16x16x32_bf16 v[2:5], v[180:183], v[212:215], v[2:5]
	s_setprio 0
	s_barrier
	s_add_i32 s69, s69, 2
	s_add_u32 s56, s56, 0x100
	s_addc_u32 s57, s57, 0
	s_add_u32 s67, s67, 0x100
	s_addc_u32 s68, s68, 0
	s_cmp_gt_u32 s69, 13
	s_cbranch_scc0 .LBB0_1474
	s_branch .Lp9_exit

; __device__ __forceinline__ unsigned pk2(float lo, float hi) { f32x2_t v = {lo, hi}; bf16x2_t b = __builtin_convertvector(v, bf16x2_t); return __builtin_bit_cast(unsigned, b); }
;     __device__ __forceinline__ void operator()(const f32x4 (&acc)[2][2][4][2], const Unit& u, int wr, int wc, int fr, int fq) const {
;         const int row0 = u.pm * BM + wr * 64 + fr, col0 = u.pn * BM + wc * 32 + 8 * fq;
;         f32x4 sv[2][2];
; #pragma unroll
;         for (int bj = 0; bj < 2; ++bj)
; #pragma unroll
;             for (int n = 0; n < 2; ++n) { sv[bj][n] = cs ? *(const f32x4*)(cs + col0 + bj * HALF + 4 * n) : (f32x4){1.f, 1.f, 1.f, 1.f}; sv[bj][n] = sv[bj][n] * sc; }
; #pragma unroll
;         for (int ai = 0; ai < 2; ++ai)
; #pragma unroll
;             for (int m = 0; m < 4; ++m) { bf16_t* rowp = O + (size_t)(row0 + ai * HALF + m * 16) * ldc + col0;
; #pragma unroll
;                 for (int bj = 0; bj < 2; ++bj) { f32x4 v0 = acc[ai][bj][m][0] * sv[bj][0], v1 = acc[ai][bj][m][1] * sv[bj][1];
;                     if (ACT == 1) {
; #pragma unroll
;                         for (int e = 0; e < 4; ++e) { const float a = fmaxf(v0[e], 0.f), b = fmaxf(v1[e], 0.f); v0[e] = a * a; v1[e] = b * b; } }
;                     u32x4 w; w.x = pk2(v0[0], v0[1]); w.y = pk2(v0[2], v0[3]); w.z = pk2(v1[0], v1[1]); w.w = pk2(v1[2], v1[3]);
;                     *(u32x4*)(rowp + bj * HALF) = w; } }
.LBB0_1477:
	s_add_u32 s8, s65, 0x40080
	s_addc_u32 s9, s49, 0
	v_lshl_add_u64 v[146:147], s[8:9], 0, v[138:139]
	s_add_i32 m0, s85, 0xc000
	s_nop 0
	global_load_lds_dwordx4 v[146:147], off
	v_lshl_add_u64 v[146:147], s[8:9], 0, v[140:141]
	s_add_i32 m0, s85, 0xe000
	s_nop 0
	global_load_lds_dwordx4 v[146:147], off
	v_mbcnt_lo_u32_b32 v152, -1, 0
	v_mbcnt_hi_u32_b32 v152, -1, v152
	s_lshl_b32 s8, s64, 8
	v_ashrrev_i32_e32 v146, 1, v152
	s_or_b32 s8, s8, s76
	v_and_b32_e32 v146, -8, v146
	v_add_u32_e32 v146, s8, v146
	s_lshl_b32 s8, s54, 8
	s_add_i32 s8, s8, s29
	v_and_or_b32 v152, v152, 15, s8
	v_ashrrev_i32_e32 v153, 31, v152
	v_ashrrev_i32_e32 v147, 31, v146
	v_lshlrev_b64 v[154:155], 13, v[152:153]
	v_max_f32_e32 v122, v122, v122
	v_max_f32_e32 v123, v123, v123
	v_lshl_add_u64 v[154:155], s[14:15], 0, v[154:155]
	v_lshlrev_b64 v[156:157], 1, v[146:147]
	v_max_f32_e32 v122, 0, v122
	v_max_f32_e32 v123, 0, v123
	v_lshl_add_u64 v[146:147], v[154:155], 0, v[156:157]
	v_pk_mul_f32 v[154:155], v[122:123], v[122:123]
	v_max_f32_e32 v123, v124, v124
	v_max_f32_e32 v126, v126, v126
	v_max_f32_e32 v127, v127, v127
	v_max_f32_e32 v122, v128, v128
	v_max_f32_e32 v124, 0, v123
	v_max_f32_e32 v123, v129, v129
	v_max_f32_e32 v125, v125, v125
	v_max_f32_e32 v126, 0, v126
	v_max_f32_e32 v127, 0, v127
	v_max_f32_e32 v122, 0, v122
	v_max_f32_e32 v123, 0, v123
	v_max_f32_e32 v125, 0, v125
	v_pk_mul_f32 v[126:127], v[126:127], v[126:127]
	v_pk_mul_f32 v[128:129], v[122:123], v[122:123]
	v_pk_mul_f32 v[158:159], v[124:125], v[124:125]
	v_max_f32_e32 v114, v114, v114
	v_max_f32_e32 v115, v115, v115
	v_cvt_pk_bf16_f32 v122, v126, v127
	v_cvt_pk_bf16_f32 v123, v128, v129
	v_cvt_pk_bf16_f32 v124, v154, v155
	v_cvt_pk_bf16_f32 v125, v158, v159
	v_max_f32_e32 v114, 0, v114
	v_max_f32_e32 v115, 0, v115
	global_store_dwordx4 v[146:147], v[122:125], off
	v_max_f32_e32 v118, v118, v118
	v_max_f32_e32 v119, v119, v119
	v_pk_mul_f32 v[122:123], v[114:115], v[114:115]
	v_max_f32_e32 v115, v116, v116
	v_max_f32_e32 v114, v120, v120
	v_max_f32_e32 v116, 0, v115
	v_max_f32_e32 v115, v121, v121
	v_max_f32_e32 v117, v117, v117
	v_max_f32_e32 v118, 0, v118
	v_max_f32_e32 v119, 0, v119
	v_max_f32_e32 v114, 0, v114
	v_max_f32_e32 v115, 0, v115
	v_max_f32_e32 v117, 0, v117
	v_pk_mul_f32 v[118:119], v[118:119], v[118:119]
	v_pk_mul_f32 v[120:121], v[114:115], v[114:115]
	v_pk_mul_f32 v[124:125], v[116:117], v[116:117]
	v_max_f32_e32 v106, v106, v106
	v_max_f32_e32 v107, v107, v107
	v_cvt_pk_bf16_f32 v114, v118, v119
	v_cvt_pk_bf16_f32 v115, v120, v121
	v_cvt_pk_bf16_f32 v116, v122, v123
	v_cvt_pk_bf16_f32 v117, v124, v125
	v_max_f32_e32 v106, 0, v106
	v_max_f32_e32 v107, 0, v107
	global_store_dwordx4 v[146:147], v[114:117], off offset:256
	v_max_f32_e32 v110, v110, v110
	v_max_f32_e32 v111, v111, v111
	v_or_b32_e32 v114, 16, v152
	v_pk_mul_f32 v[116:117], v[106:107], v[106:107]
	v_max_f32_e32 v107, v108, v108
	v_ashrrev_i32_e32 v115, 31, v114
	v_max_f32_e32 v106, v112, v112
	v_max_f32_e32 v108, 0, v107
	v_max_f32_e32 v107, v113, v113
	v_max_f32_e32 v109, v109, v109
	v_lshlrev_b64 v[114:115], 13, v[114:115]
	v_max_f32_e32 v110, 0, v110
	v_max_f32_e32 v111, 0, v111
	v_max_f32_e32 v106, 0, v106
	v_max_f32_e32 v107, 0, v107
	v_max_f32_e32 v109, 0, v109
	v_lshl_add_u64 v[114:115], s[14:15], 0, v[114:115]
	v_pk_mul_f32 v[110:111], v[110:111], v[110:111]
	v_pk_mul_f32 v[112:113], v[106:107], v[106:107]
	v_pk_mul_f32 v[118:119], v[108:109], v[108:109]
	v_max_f32_e32 v98, v98, v98
	v_max_f32_e32 v99, v99, v99
	v_lshl_add_u64 v[114:115], v[114:115], 0, v[156:157]
	v_cvt_pk_bf16_f32 v106, v110, v111
	v_cvt_pk_bf16_f32 v107, v112, v113
	v_cvt_pk_bf16_f32 v108, v116, v117
	v_cvt_pk_bf16_f32 v109, v118, v119
	v_max_f32_e32 v98, 0, v98
	v_max_f32_e32 v99, 0, v99
	global_store_dwordx4 v[114:115], v[106:109], off
	v_max_f32_e32 v102, v102, v102
	v_max_f32_e32 v103, v103, v103
	v_pk_mul_f32 v[106:107], v[98:99], v[98:99]
	v_max_f32_e32 v99, v100, v100
	v_max_f32_e32 v98, v104, v104
	v_max_f32_e32 v100, 0, v99
	v_max_f32_e32 v99, v105, v105
	v_max_f32_e32 v101, v101, v101
	v_max_f32_e32 v102, 0, v102
	v_max_f32_e32 v103, 0, v103
	v_max_f32_e32 v98, 0, v98
	v_max_f32_e32 v99, 0, v99
	v_max_f32_e32 v101, 0, v101
	v_pk_mul_f32 v[102:103], v[102:103], v[102:103]
	v_pk_mul_f32 v[104:105], v[98:99], v[98:99]
	v_pk_mul_f32 v[108:109], v[100:101], v[100:101]
	v_max_f32_e32 v90, v90, v90
	v_max_f32_e32 v91, v91, v91
	v_cvt_pk_bf16_f32 v98, v102, v103
	v_cvt_pk_bf16_f32 v99, v104, v105
	v_cvt_pk_bf16_f32 v100, v106, v107
	v_cvt_pk_bf16_f32 v101, v108, v109
	v_max_f32_e32 v90, 0, v90
	v_max_f32_e32 v91, 0, v91
	global_store_dwordx4 v[114:115], v[98:101], off offset:256
	v_max_f32_e32 v94, v94, v94
	v_max_f32_e32 v95, v95, v95
	v_or_b32_e32 v98, 32, v152
	v_pk_mul_f32 v[100:101], v[90:91], v[90:91]
	v_max_f32_e32 v91, v92, v92
	v_ashrrev_i32_e32 v99, 31, v98
	v_max_f32_e32 v90, v96, v96
	v_max_f32_e32 v92, 0, v91
	v_max_f32_e32 v91, v97, v97
	v_max_f32_e32 v93, v93, v93
	v_lshlrev_b64 v[98:99], 13, v[98:99]
	v_max_f32_e32 v94, 0, v94
	v_max_f32_e32 v95, 0, v95
	v_max_f32_e32 v90, 0, v90
	v_max_f32_e32 v91, 0, v91
	v_max_f32_e32 v93, 0, v93
	v_lshl_add_u64 v[98:99], s[14:15], 0, v[98:99]
	v_pk_mul_f32 v[94:95], v[94:95], v[94:95]
	v_pk_mul_f32 v[96:97], v[90:91], v[90:91]
	v_pk_mul_f32 v[102:103], v[92:93], v[92:93]
	v_max_f32_e32 v82, v82, v82
	v_max_f32_e32 v83, v83, v83
	v_lshl_add_u64 v[98:99], v[98:99], 0, v[156:157]
	v_cvt_pk_bf16_f32 v90, v94, v95
	v_cvt_pk_bf16_f32 v91, v96, v97
	v_cvt_pk_bf16_f32 v92, v100, v101
	v_cvt_pk_bf16_f32 v93, v102, v103
	v_max_f32_e32 v82, 0, v82
	v_max_f32_e32 v83, 0, v83
; __device__ __forceinline__ unsigned pk2(float lo, float hi) { f32x2_t v = {lo, hi}; bf16x2_t b = __builtin_convertvector(v, bf16x2_t); return __builtin_bit_cast(unsigned, b); }
;     __device__ __forceinline__ void operator()(const f32x4 (&acc)[2][2][4][2], const Unit& u, int wr, int wc, int fr, int fq) const {
;     ...
;         for (int ai = 0; ai < 2; ++ai)
; #pragma unroll
;             for (int m = 0; m < 4; ++m) { bf16_t* rowp = O + (size_t)(row0 + ai * HALF + m * 16) * ldc + col0;
; #pragma unroll
;                 for (int bj = 0; bj < 2; ++bj) { f32x4 v0 = acc[ai][bj][m][0] * sv[bj][0], v1 = acc[ai][bj][m][1] * sv[bj][1];
;                     if (ACT == 1) {
; #pragma unroll
;                         for (int e = 0; e < 4; ++e) { const float a = fmaxf(v0[e], 0.f), b = fmaxf(v1[e], 0.f); v0[e] = a * a; v1[e] = b * b; } }
;                     u32x4 w; w.x = pk2(v0[0], v0[1]); w.y = pk2(v0[2], v0[3]); w.z = pk2(v1[0], v1[1]); w.w = pk2(v1[2], v1[3]);
;                     *(u32x4*)(rowp + bj * HALF) = w; } }
	global_store_dwordx4 v[98:99], v[90:93], off
	v_max_f32_e32 v86, v86, v86
	v_max_f32_e32 v87, v87, v87
	v_pk_mul_f32 v[90:91], v[82:83], v[82:83]
	v_max_f32_e32 v83, v84, v84
	v_max_f32_e32 v82, v88, v88
	v_max_f32_e32 v84, 0, v83
	v_max_f32_e32 v83, v89, v89
	v_max_f32_e32 v85, v85, v85
	v_max_f32_e32 v86, 0, v86
	v_max_f32_e32 v87, 0, v87
	v_max_f32_e32 v82, 0, v82
	v_max_f32_e32 v83, 0, v83
	v_max_f32_e32 v85, 0, v85
	v_pk_mul_f32 v[86:87], v[86:87], v[86:87]
	v_pk_mul_f32 v[88:89], v[82:83], v[82:83]
	v_pk_mul_f32 v[92:93], v[84:85], v[84:85]
	v_max_f32_e32 v74, v74, v74
	v_max_f32_e32 v75, v75, v75
	v_cvt_pk_bf16_f32 v82, v86, v87
	v_cvt_pk_bf16_f32 v83, v88, v89
	v_cvt_pk_bf16_f32 v84, v90, v91
	v_cvt_pk_bf16_f32 v85, v92, v93
	v_max_f32_e32 v74, 0, v74
	v_max_f32_e32 v75, 0, v75
	global_store_dwordx4 v[98:99], v[82:85], off offset:256
	v_max_f32_e32 v78, v78, v78
	v_max_f32_e32 v79, v79, v79
	v_or_b32_e32 v82, 48, v152
	v_pk_mul_f32 v[84:85], v[74:75], v[74:75]
	v_max_f32_e32 v75, v76, v76
	v_ashrrev_i32_e32 v83, 31, v82
	v_max_f32_e32 v74, v80, v80
	v_max_f32_e32 v76, 0, v75
	v_max_f32_e32 v75, v81, v81
	v_max_f32_e32 v77, v77, v77
	v_lshlrev_b64 v[82:83], 13, v[82:83]
	v_max_f32_e32 v78, 0, v78
	v_max_f32_e32 v79, 0, v79
	v_max_f32_e32 v74, 0, v74
	v_max_f32_e32 v75, 0, v75
	v_max_f32_e32 v77, 0, v77
	v_lshl_add_u64 v[82:83], s[14:15], 0, v[82:83]
	v_pk_mul_f32 v[78:79], v[78:79], v[78:79]
	v_pk_mul_f32 v[80:81], v[74:75], v[74:75]
	v_pk_mul_f32 v[86:87], v[76:77], v[76:77]
	v_max_f32_e32 v66, v66, v66
	v_max_f32_e32 v67, v67, v67
	v_lshl_add_u64 v[82:83], v[82:83], 0, v[156:157]
	v_cvt_pk_bf16_f32 v74, v78, v79
	v_cvt_pk_bf16_f32 v75, v80, v81
	v_cvt_pk_bf16_f32 v76, v84, v85
	v_cvt_pk_bf16_f32 v77, v86, v87
	v_max_f32_e32 v66, 0, v66
	v_max_f32_e32 v67, 0, v67
	global_store_dwordx4 v[82:83], v[74:77], off
	v_max_f32_e32 v70, v70, v70
	v_max_f32_e32 v71, v71, v71
	v_pk_mul_f32 v[74:75], v[66:67], v[66:67]
	v_max_f32_e32 v67, v68, v68
	v_max_f32_e32 v66, v72, v72
	v_max_f32_e32 v68, 0, v67
	v_max_f32_e32 v67, v73, v73
	v_max_f32_e32 v69, v69, v69
	v_max_f32_e32 v70, 0, v70
	v_max_f32_e32 v71, 0, v71
	v_max_f32_e32 v66, 0, v66
	v_max_f32_e32 v67, 0, v67
	v_max_f32_e32 v69, 0, v69
	v_pk_mul_f32 v[70:71], v[70:71], v[70:71]
	v_pk_mul_f32 v[72:73], v[66:67], v[66:67]
	v_pk_mul_f32 v[76:77], v[68:69], v[68:69]
	v_max_f32_e32 v58, v58, v58
	v_max_f32_e32 v59, v59, v59
	v_cvt_pk_bf16_f32 v66, v70, v71
	v_cvt_pk_bf16_f32 v67, v72, v73
	v_cvt_pk_bf16_f32 v68, v74, v75
	v_cvt_pk_bf16_f32 v69, v76, v77
	v_max_f32_e32 v58, 0, v58
	v_max_f32_e32 v59, 0, v59
	global_store_dwordx4 v[82:83], v[66:69], off offset:256
	v_max_f32_e32 v62, v62, v62
	v_max_f32_e32 v63, v63, v63
	v_pk_mul_f32 v[68:69], v[58:59], v[58:59]
	v_max_f32_e32 v59, v60, v60
	v_max_f32_e32 v62, 0, v62
	v_max_f32_e32 v63, 0, v63
	v_max_f32_e32 v58, v64, v64
	v_max_f32_e32 v60, 0, v59
	v_max_f32_e32 v59, v65, v65
	v_max_f32_e32 v61, v61, v61
	v_pk_mul_f32 v[62:63], v[62:63], v[62:63]
	v_max_f32_e32 v58, 0, v58
	v_max_f32_e32 v59, 0, v59
	v_max_f32_e32 v61, 0, v61
	v_pk_mul_f32 v[64:65], v[58:59], v[58:59]
	v_pk_mul_f32 v[70:71], v[60:61], v[60:61]
	v_cvt_pk_bf16_f32 v58, v62, v63
	v_add_co_u32_e32 v62, vcc, s37, v146
	v_max_f32_e32 v50, v50, v50
	v_max_f32_e32 v51, v51, v51
	v_cvt_pk_bf16_f32 v59, v64, v65
	v_cvt_pk_bf16_f32 v60, v68, v69
	v_cvt_pk_bf16_f32 v61, v70, v71
	v_addc_co_u32_e32 v63, vcc, 0, v147, vcc
	v_max_f32_e32 v50, 0, v50
	v_max_f32_e32 v51, 0, v51
	global_store_dwordx4 v[62:63], v[58:61], off
	v_max_f32_e32 v54, v54, v54
	v_max_f32_e32 v55, v55, v55
	v_pk_mul_f32 v[58:59], v[50:51], v[50:51]
	v_max_f32_e32 v51, v52, v52
	v_max_f32_e32 v50, v56, v56
	v_max_f32_e32 v52, 0, v51
	v_max_f32_e32 v51, v57, v57
	v_max_f32_e32 v53, v53, v53
	v_max_f32_e32 v54, 0, v54
	v_max_f32_e32 v55, 0, v55
	v_max_f32_e32 v50, 0, v50
	v_max_f32_e32 v51, 0, v51
	v_max_f32_e32 v53, 0, v53
	v_pk_mul_f32 v[54:55], v[54:55], v[54:55]
	v_pk_mul_f32 v[56:57], v[50:51], v[50:51]
	v_pk_mul_f32 v[60:61], v[52:53], v[52:53]
	v_max_f32_e32 v42, v42, v42
	v_max_f32_e32 v43, v43, v43
	v_lshl_add_u64 v[66:67], v[146:147], 0, s[38:39]
	v_cvt_pk_bf16_f32 v50, v54, v55
	v_cvt_pk_bf16_f32 v51, v56, v57
	v_cvt_pk_bf16_f32 v52, v58, v59
	v_cvt_pk_bf16_f32 v53, v60, v61
	v_max_f32_e32 v42, 0, v42
	v_max_f32_e32 v43, 0, v43
	global_store_dwordx4 v[66:67], v[50:53], off offset:256
	v_max_f32_e32 v46, v46, v46
	v_max_f32_e32 v47, v47, v47
	v_pk_mul_f32 v[52:53], v[42:43], v[42:43]
	v_max_f32_e32 v43, v44, v44
	v_max_f32_e32 v46, 0, v46
	v_max_f32_e32 v47, 0, v47
	v_max_f32_e32 v42, v48, v48
	v_max_f32_e32 v44, 0, v43
	v_max_f32_e32 v43, v49, v49
	v_max_f32_e32 v45, v45, v45
	v_pk_mul_f32 v[46:47], v[46:47], v[46:47]
	v_max_f32_e32 v42, 0, v42
	v_max_f32_e32 v43, 0, v43
	v_max_f32_e32 v45, 0, v45
; #define PG8_BAR __builtin_amdgcn_s_barrier()
; __device__ __forceinline__ unsigned pk2(float lo, float hi) { f32x2_t v = {lo, hi}; bf16x2_t b = __builtin_convertvector(v, bf16x2_t); return __builtin_bit_cast(unsigned, b); }
; template <class Epi, class Sched, bool ALIGN_EPI = false, bool SP2 = false>
; __device__ __forceinline__ void gemm_phase(PG8_LAS unsigned char* lds, const Gemm g, const Sched& S, const Epi& E, const int wid) {
;     ...
;         cur = nxt; cA = nA; cB = nB; ++ui;
;         if constexpr (ALIGN_EPI) { if (wr == 1) PG8_BAR; }
;     }
;     __device__ __forceinline__ void operator()(const f32x4 (&acc)[2][2][4][2], const Unit& u, int wr, int wc, int fr, int fq) const {
;     ...
;             for (int m = 0; m < 4; ++m) { bf16_t* rowp = O + (size_t)(row0 + ai * HALF + m * 16) * ldc + col0;
; #pragma unroll
;                 for (int bj = 0; bj < 2; ++bj) { f32x4 v0 = acc[ai][bj][m][0] * sv[bj][0], v1 = acc[ai][bj][m][1] * sv[bj][1];
;                     if (ACT == 1) {
; #pragma unroll
;                         for (int e = 0; e < 4; ++e) { const float a = fmaxf(v0[e], 0.f), b = fmaxf(v1[e], 0.f); v0[e] = a * a; v1[e] = b * b; } }
;                     u32x4 w; w.x = pk2(v0[0], v0[1]); w.y = pk2(v0[2], v0[3]); w.z = pk2(v1[0], v1[1]); w.w = pk2(v1[2], v1[3]);
;                     *(u32x4*)(rowp + bj * HALF) = w; } }
	v_pk_mul_f32 v[48:49], v[42:43], v[42:43]
	v_pk_mul_f32 v[54:55], v[44:45], v[44:45]
	v_cvt_pk_bf16_f32 v42, v46, v47
	v_add_co_u32_e32 v46, vcc, s55, v146
	v_max_f32_e32 v34, v34, v34
	v_max_f32_e32 v35, v35, v35
	v_cvt_pk_bf16_f32 v43, v48, v49
	v_cvt_pk_bf16_f32 v44, v52, v53
	v_cvt_pk_bf16_f32 v45, v54, v55
	v_addc_co_u32_e32 v47, vcc, 0, v147, vcc
	v_max_f32_e32 v34, 0, v34
	v_max_f32_e32 v35, 0, v35
	global_store_dwordx4 v[46:47], v[42:45], off
	v_max_f32_e32 v38, v38, v38
	v_max_f32_e32 v39, v39, v39
	v_pk_mul_f32 v[42:43], v[34:35], v[34:35]
	v_max_f32_e32 v35, v36, v36
	v_max_f32_e32 v34, v40, v40
	v_max_f32_e32 v36, 0, v35
	v_max_f32_e32 v35, v41, v41
	v_max_f32_e32 v37, v37, v37
	v_max_f32_e32 v38, 0, v38
	v_max_f32_e32 v39, 0, v39
	v_max_f32_e32 v34, 0, v34
	v_max_f32_e32 v35, 0, v35
	v_max_f32_e32 v37, 0, v37
	v_pk_mul_f32 v[38:39], v[38:39], v[38:39]
	v_pk_mul_f32 v[40:41], v[34:35], v[34:35]
	v_pk_mul_f32 v[44:45], v[36:37], v[36:37]
	v_max_f32_e32 v26, v26, v26
	v_max_f32_e32 v27, v27, v27
	v_lshl_add_u64 v[50:51], v[146:147], 0, s[40:41]
	v_cvt_pk_bf16_f32 v34, v38, v39
	v_cvt_pk_bf16_f32 v35, v40, v41
	v_cvt_pk_bf16_f32 v36, v42, v43
	v_cvt_pk_bf16_f32 v37, v44, v45
	v_max_f32_e32 v26, 0, v26
	v_max_f32_e32 v27, 0, v27
	global_store_dwordx4 v[50:51], v[34:37], off offset:256
	v_max_f32_e32 v30, v30, v30
	v_max_f32_e32 v31, v31, v31
	v_pk_mul_f32 v[36:37], v[26:27], v[26:27]
	v_max_f32_e32 v27, v28, v28
	v_max_f32_e32 v30, 0, v30
	v_max_f32_e32 v31, 0, v31
	v_max_f32_e32 v26, v32, v32
	v_max_f32_e32 v28, 0, v27
	v_max_f32_e32 v27, v33, v33
	v_max_f32_e32 v29, v29, v29
	v_pk_mul_f32 v[30:31], v[30:31], v[30:31]
	v_max_f32_e32 v26, 0, v26
	v_max_f32_e32 v27, 0, v27
	v_max_f32_e32 v29, 0, v29
	v_pk_mul_f32 v[32:33], v[26:27], v[26:27]
	v_pk_mul_f32 v[38:39], v[28:29], v[28:29]
	v_cvt_pk_bf16_f32 v26, v30, v31
	v_add_co_u32_e32 v30, vcc, s62, v146
	v_max_f32_e32 v18, v18, v18
	v_max_f32_e32 v19, v19, v19
	v_cvt_pk_bf16_f32 v27, v32, v33
	v_cvt_pk_bf16_f32 v28, v36, v37
	v_cvt_pk_bf16_f32 v29, v38, v39
	v_addc_co_u32_e32 v31, vcc, 0, v147, vcc
	v_max_f32_e32 v18, 0, v18
	v_max_f32_e32 v19, 0, v19
	global_store_dwordx4 v[30:31], v[26:29], off
	v_max_f32_e32 v22, v22, v22
	v_max_f32_e32 v23, v23, v23
	v_pk_mul_f32 v[26:27], v[18:19], v[18:19]
	v_max_f32_e32 v19, v20, v20
	v_max_f32_e32 v18, v24, v24
	v_max_f32_e32 v20, 0, v19
	v_max_f32_e32 v19, v25, v25
	v_max_f32_e32 v21, v21, v21
	v_max_f32_e32 v22, 0, v22
	v_max_f32_e32 v23, 0, v23
	v_max_f32_e32 v18, 0, v18
	v_max_f32_e32 v19, 0, v19
	v_max_f32_e32 v21, 0, v21
	v_pk_mul_f32 v[22:23], v[22:23], v[22:23]
	v_pk_mul_f32 v[24:25], v[18:19], v[18:19]
	v_pk_mul_f32 v[28:29], v[20:21], v[20:21]
	v_max_f32_e32 v10, v10, v10
	v_max_f32_e32 v11, v11, v11
	v_lshl_add_u64 v[34:35], v[146:147], 0, s[42:43]
	v_cvt_pk_bf16_f32 v18, v22, v23
	v_cvt_pk_bf16_f32 v19, v24, v25
	v_cvt_pk_bf16_f32 v20, v26, v27
	v_cvt_pk_bf16_f32 v21, v28, v29
	v_max_f32_e32 v10, 0, v10
	v_max_f32_e32 v11, 0, v11
	global_store_dwordx4 v[34:35], v[18:21], off offset:256
	v_max_f32_e32 v14, v14, v14
	v_max_f32_e32 v15, v15, v15
	v_pk_mul_f32 v[20:21], v[10:11], v[10:11]
	v_max_f32_e32 v11, v12, v12
	v_max_f32_e32 v14, 0, v14
	v_max_f32_e32 v15, 0, v15
	v_max_f32_e32 v10, v16, v16
	v_max_f32_e32 v12, 0, v11
	v_max_f32_e32 v11, v17, v17
	v_max_f32_e32 v13, v13, v13
	v_pk_mul_f32 v[14:15], v[14:15], v[14:15]
	v_max_f32_e32 v10, 0, v10
	v_max_f32_e32 v11, 0, v11
	v_max_f32_e32 v13, 0, v13
	v_pk_mul_f32 v[16:17], v[10:11], v[10:11]
	v_pk_mul_f32 v[22:23], v[12:13], v[12:13]
	v_cvt_pk_bf16_f32 v10, v14, v15
	v_add_co_u32_e32 v14, vcc, s63, v146
	v_max_f32_e32 v2, v2, v2
	v_max_f32_e32 v3, v3, v3
	v_cvt_pk_bf16_f32 v11, v16, v17
	v_cvt_pk_bf16_f32 v12, v20, v21
	v_cvt_pk_bf16_f32 v13, v22, v23
	v_addc_co_u32_e32 v15, vcc, 0, v147, vcc
	v_max_f32_e32 v2, 0, v2
	v_max_f32_e32 v3, 0, v3
	global_store_dwordx4 v[14:15], v[10:13], off
	v_max_f32_e32 v6, v6, v6
	v_max_f32_e32 v7, v7, v7
	v_pk_mul_f32 v[10:11], v[2:3], v[2:3]
	v_max_f32_e32 v3, v4, v4
	v_max_f32_e32 v2, v8, v8
	v_max_f32_e32 v4, 0, v3
	v_max_f32_e32 v3, v9, v9
	v_max_f32_e32 v5, v5, v5
	v_max_f32_e32 v6, 0, v6
	v_max_f32_e32 v7, 0, v7
	v_max_f32_e32 v2, 0, v2
	v_max_f32_e32 v3, 0, v3
	v_max_f32_e32 v5, 0, v5
	v_pk_mul_f32 v[6:7], v[6:7], v[6:7]
	v_pk_mul_f32 v[8:9], v[2:3], v[2:3]
	v_pk_mul_f32 v[12:13], v[4:5], v[4:5]
	v_lshl_add_u64 v[18:19], v[146:147], 0, s[44:45]
	v_cvt_pk_bf16_f32 v2, v6, v7
	v_cvt_pk_bf16_f32 v3, v8, v9
	v_cvt_pk_bf16_f32 v4, v10, v11
	v_cvt_pk_bf16_f32 v5, v12, v13
	s_andn2_b64 vcc, exec, s[12:13]
	s_mov_b64 s[12:13], -1
	global_store_dwordx4 v[18:19], v[2:5], off offset:256
	s_cbranch_vccnz .LBB0_1470
	v_readlane_b32 s8, v237, 4
	v_readlane_b32 s9, v237, 5
	s_and_b64 vcc, exec, s[8:9]
	s_cbranch_vccnz .LBB0_1469
	s_barrier
	s_branch .LBB0_1469
